# gMLP: bias and first-chunk u/gate loads of step C issued before step B (new registers, step-B waits counted +5) so their HBM latency overlaps the normalise step
# speedup vs baseline: 1.0103x; 1.0103x over previous
; #define LAS __attribute__((address_space(3)))
; __device__ __forceinline__ u32x4 pack8(f32x4 a, f32x4 b) { u32x4 w; w.x = pk2(a[0], a[1]); w.y = pk2(a[2], a[3]); w.z = pk2(b[0], b[1]); w.w = pk2(b[2], b[3]); return w; }
; __device__ __forceinline__ void gmlp_task(LAS unsigned char* lds, const Params& p, const bf16_t* P, bf16_t* Y, const float* svg, float* ssb, int l, bool sample, int b, int g, int q, int tid, int wave, int lane, bool load_ws = true) {
;     ...
;             const f32x2 mr = MUR[sub * 128 + j];
;             const float mean = mr.x, rstd = mr.y;
;             const u32x4 w = wraw[sub][k];
;             const f32x4 g0 = *(const f32x4*)(lg + ch * 8), g1 = *(const f32x4*)(lg + ch * 8 + 4), b0 = *(const f32x4*)(lb + ch * 8), b1 = *(const f32x4*)(lb + ch * 8 + 4);
;             f32x4 v0 = (f32x4){bf_lo(w.x), bf_hi(w.x), bf_lo(w.y), bf_hi(w.y)}, v1 = (f32x4){bf_lo(w.z), bf_hi(w.z), bf_lo(w.w), bf_hi(w.w)};
;             v0 = (v0 - mean) * rstd * g0 + b0; v1 = (v1 - mean) * rstd * g1 + b1;
;             if (sample) { float* dst = p.out + OUT_VGS + ((((size_t)l * 32 + cidx) * 32 + j) * 16 + g) * 64 + ch * 8; *(f32x4*)dst = v0; *(f32x4*)(dst + 4) = v1; }
;             *(LAS u32x4*)(VGT + j * 72 + ch * 8) = pack8(v0, v1);
;     ...
;         const int i = 32 * it + r;
;         const float bias = p.b_spatial[(l * 16 + g) * 128 + i];
;         const int nks = 2 * (it + 1);
; #pragma unroll
;         for (int sub = 0; sub < 4; ++sub) {
;             const int cidx = q * 4 + sub;
;             const size_t row0 = sample ? (size_t)NP + cidx * 32 : (size_t)b * 2048 + cidx * 128;
;             const LAS bf16_t* VGT = (const LAS bf16_t*)(lds + vgt_off(sub));
;             const size_t row = row0 + i;
;             const bf16_t* up = P + row * DPROJ + O_U + g * 64 + 32 * dt + 8 * h;
;             const bf16_t* gp = P + row * DPROJ + O_GB + g * 64 + 32 * dt + 8 * h;
;             u32x4 uw[2], gw[2];
; #pragma unroll
;             for (int pr = 0; pr < 2; ++pr) { uw[pr] = *(const u32x4*)(up + 16 * pr); gw[pr] = *(const u32x4*)(gp + 16 * pr); }
.LBB0_478:
	s_or_b64 exec, exec, s[16:17]
	s_lshl_b64 s[16:17], s[0:1], 2
	s_add_u32 s18, s25, s16
	s_addc_u32 s19, s26, s17
	s_add_u32 s16, s23, s16
	s_addc_u32 s17, s24, s17
	v_lshlrev_b32_e32 v0, 2, v46
	v_and_b32_e32 v39, -8, v44
	s_waitcnt lgkmcnt(0)
	v_lshl_add_u64 v[36:37], s[18:19], 0, v[0:1]
	v_lshl_add_u64 v[34:35], s[16:17], 0, v[0:1]
	global_load_dwordx4 v[192:195], v[36:37], off offset:16
	global_load_dwordx4 v[196:199], v[36:37], off
	global_load_dwordx4 v[200:203], v[34:35], off offset:16
	global_load_dwordx4 v[204:207], v[34:35], off
	v_and_b32_e32 v124, 31, v42
	v_readlane_b32 s4, v253, 39
	s_lshl_b32 s11, s33, 7
	s_add_i32 s11, s11, s22
	s_nop 0
	v_or_b32_e32 v124, s4, v124
	v_add_u32_e32 v126, s11, v124
	v_ashrrev_i32_e32 v127, 31, v126
	v_lshl_add_u64 v[126:127], v[126:127], 2, s[64:65]
	global_load_dword v168, v[126:127], off
	v_add_u32_e32 v125, s44, v124
	v_mov_b64_e32 v[128:129], s[68:69]
	v_mad_u64_u32 v[128:129], vcc, v125, s73, v[128:129]
	v_readlane_b32 s4, v253, 40
	v_ashrrev_i32_e32 v130, 2, v42
	v_and_b32_e32 v130, -8, v130
	s_nop 0
	s_lshl_b32 s18, s4, 1
	s_mov_b32 s19, 0
	v_lshl_add_u64 v[128:129], s[0:1], 1, v[128:129]
	v_ashrrev_i32_e32 v131, 31, v130
	v_lshl_add_u64 v[128:129], v[128:129], 0, s[18:19]
	v_lshl_add_u64 v[128:129], v[130:131], 1, v[128:129]
	s_mov_b64 s[16:17], 0x1000
	v_lshl_add_u64 v[126:127], v[128:129], 0, s[16:17]
	global_load_dwordx4 v[164:167], v[126:127], off offset:1024
	s_mov_b64 s[16:17], 0x2000
	v_lshl_add_u64 v[126:127], v[128:129], 0, s[16:17]
	global_load_dwordx4 v[160:163], v[126:127], off offset:1024
	s_mov_b64 s[16:17], 0x1400
	v_lshl_add_u64 v[126:127], v[128:129], 0, s[16:17]
	global_load_dwordx4 v[156:159], v[126:127], off offset:32
	s_mov_b64 s[16:17], 0x2400
	v_lshl_add_u64 v[126:127], v[128:129], 0, s[16:17]
	global_load_dwordx4 v[152:155], v[126:127], off offset:32
	v_lshl_add_u32 v0, v46, 1, 0
	v_lshrrev_b32_e32 v38, 3, v44
	v_add_u32_e32 v39, 0, v39
	s_barrier
	s_and_saveexec_b64 s[16:17], s[42:43]
	s_cbranch_execz .LBB0_480
	v_add_u32_e32 v40, 0x1a800, v39
	ds_read_b64 v[40:41], v40
	s_waitcnt vmcnt(9)
	v_lshlrev_b32_e32 v44, 16, v30
	v_and_b32_e32 v62, 0xffff0000, v30
	v_lshlrev_b32_e32 v30, 16, v31
	v_and_b32_e32 v31, 0xffff0000, v31
	v_lshlrev_b32_e32 v63, 16, v32
	v_and_b32_e32 v64, 0xffff0000, v32
	v_lshlrev_b32_e32 v65, 16, v33
	v_and_b32_e32 v66, 0xffff0000, v33
	s_waitcnt lgkmcnt(0)
	v_sub_f32_e32 v31, v31, v40
	v_sub_f32_e32 v30, v30, v40
	v_sub_f32_e32 v33, v62, v40
	v_sub_f32_e32 v32, v44, v40
	v_pk_mul_f32 v[32:33], v[40:41], v[32:33] op_sel:[1,0]
	v_pk_mul_f32 v[30:31], v[40:41], v[30:31] op_sel:[1,0]
	s_waitcnt vmcnt(5)
	v_pk_fma_f32 v[52:53], v[198:199], v[30:31], v[206:207]
	v_pk_fma_f32 v[30:31], v[196:197], v[32:33], v[204:205]
	v_sub_f32_e32 v33, v66, v40
	v_sub_f32_e32 v32, v65, v40
	v_sub_f32_e32 v51, v64, v40
	v_sub_f32_e32 v50, v63, v40
	v_pk_mul_f32 v[50:51], v[40:41], v[50:51] op_sel:[1,0]
	v_pk_mul_f32 v[32:33], v[40:41], v[32:33] op_sel:[1,0]
	v_cvt_pk_bf16_f32 v30, v30, v31
	v_pk_fma_f32 v[40:41], v[194:195], v[32:33], v[202:203]
	v_pk_fma_f32 v[32:33], v[192:193], v[50:51], v[200:201]
	v_cvt_pk_bf16_f32 v31, v52, v53
	v_cvt_pk_bf16_f32 v32, v32, v33
	v_cvt_pk_bf16_f32 v33, v40, v41
	v_mad_u64_u32 v[40:41], s[18:19], v38, s89, v[0:1]
	ds_write_b128 v40, v[30:33]
.LBB0_480:
	s_or_b64 exec, exec, s[16:17]
	s_waitcnt vmcnt(5)
	v_and_b32_e32 v31, -8, v43
	v_lshrrev_b32_e32 v30, 3, v43
	v_add_u32_e32 v31, 0, v31
	s_and_saveexec_b64 s[16:17], s[40:41]
	s_cbranch_execnz .LBB0_504
	s_or_b64 exec, exec, s[16:17]
	s_and_saveexec_b64 s[16:17], s[42:43]
	s_cbranch_execnz .LBB0_505

; #define LAS __attribute__((address_space(3)))
; __device__ __forceinline__ void gmlp_task(LAS unsigned char* lds, const Params& p, const bf16_t* P, bf16_t* Y, const float* svg, float* ssb, int l, bool sample, int b, int g, int q, int tid, int wave, int lane, bool load_ws = true) {
;     ...
;             const int ch = id & 7, j = id >> 3;
;             const f32x2 mr = MUR[sub * 128 + j];
;             const float mean = mr.x, rstd = mr.y;
;             const u32x4 w = wraw[sub][k];
;             const f32x4 g0 = *(const f32x4*)(lg + ch * 8), g1 = *(const f32x4*)(lg + ch * 8 + 4), b0 = *(const f32x4*)(lb + ch * 8), b1 = *(const f32x4*)(lb + ch * 8 + 4);
;             f32x4 v0 = (f32x4){bf_lo(w.x), bf_hi(w.x), bf_lo(w.y), bf_hi(w.y)}, v1 = (f32x4){bf_lo(w.z), bf_hi(w.z), bf_lo(w.w), bf_hi(w.w)};
;             v0 = (v0 - mean) * rstd * g0 + b0; v1 = (v1 - mean) * rstd * g1 + b1;
;             if (sample) { float* dst = p.out + OUT_VGS + ((((size_t)l * 32 + cidx) * 32 + j) * 16 + g) * 64 + ch * 8; *(f32x4*)dst = v0; *(f32x4*)(dst + 4) = v1; }
;             *(LAS u32x4*)(VGT + j * 72 + ch * 8) = pack8(v0, v1);
;         }
;     }
;     __syncthreads();
;     const int it = sample ? 0 : (wave >> 1), dt = wave & 1;
;     const bool active = sample ? (wave < 2) : true;
;     if (active) {
;         const int i = 32 * it + r;
;         const float bias = p.b_spatial[(l * 16 + g) * 128 + i];
;         const int nks = 2 * (it + 1);
; #pragma unroll
;         for (int sub = 0; sub < 4; ++sub) {
;             const int cidx = q * 4 + sub;
;             const size_t row0 = sample ? (size_t)NP + cidx * 32 : (size_t)b * 2048 + cidx * 128;
;             const LAS bf16_t* VGT = (const LAS bf16_t*)(lds + vgt_off(sub));
;             const size_t row = row0 + i;
;             const bf16_t* up = P + row * DPROJ + O_U + g * 64 + 32 * dt + 8 * h;
;             const bf16_t* gp = P + row * DPROJ + O_GB + g * 64 + 32 * dt + 8 * h;
;             u32x4 uw[2], gw[2];
; #pragma unroll
;             for (int pr = 0; pr < 2; ++pr) { uw[pr] = *(const u32x4*)(up + 16 * pr); gw[pr] = *(const u32x4*)(gp + 16 * pr); }
;             f32x16 acc;
; #pragma unroll
;             for (int e = 0; e < 16; ++e) acc[e] = 0.f;
;             const LAS bf16_t* tr = VGT + (8 * h + ((lane & 15) >> 2)) * 72 + 32 * dt + 16 * ((lane >> 4) & 1) + 4 * (lane & 3);
;             for (int ks = 0; ks < nks; ++ks) {
.LBB0_487:
	v_add_u32_e32 v6, 0x1b400, v31
	ds_read_b64 v[22:23], v6
	v_lshlrev_b32_e32 v24, 16, v2
	v_and_b32_e32 v25, 0xffff0000, v2
	v_lshlrev_b32_e32 v2, 16, v3
	v_and_b32_e32 v3, 0xffff0000, v3
	v_lshlrev_b32_e32 v26, 16, v4
	v_and_b32_e32 v27, 0xffff0000, v4
	v_lshlrev_b32_e32 v28, 16, v5
	v_and_b32_e32 v29, 0xffff0000, v5
	s_waitcnt lgkmcnt(0)
	v_sub_f32_e32 v3, v3, v22
	v_sub_f32_e32 v2, v2, v22
	v_sub_f32_e32 v5, v25, v22
	v_sub_f32_e32 v4, v24, v22
	v_pk_mul_f32 v[4:5], v[22:23], v[4:5] op_sel:[1,0]
	v_pk_mul_f32 v[2:3], v[22:23], v[2:3] op_sel:[1,0]
	s_waitcnt vmcnt(5)
	v_pk_fma_f32 v[12:13], v[198:199], v[2:3], v[206:207]
	v_pk_fma_f32 v[2:3], v[196:197], v[4:5], v[204:205]
	v_sub_f32_e32 v5, v29, v22
	v_sub_f32_e32 v4, v28, v22
	v_sub_f32_e32 v11, v27, v22
	v_sub_f32_e32 v10, v26, v22
	v_pk_mul_f32 v[10:11], v[22:23], v[10:11] op_sel:[1,0]
	v_pk_mul_f32 v[4:5], v[22:23], v[4:5] op_sel:[1,0]
	v_cvt_pk_bf16_f32 v2, v2, v3
	v_pk_fma_f32 v[8:9], v[194:195], v[4:5], v[202:203]
	v_pk_fma_f32 v[4:5], v[192:193], v[10:11], v[200:201]
	v_cvt_pk_bf16_f32 v3, v12, v13
	v_cvt_pk_bf16_f32 v4, v4, v5
	v_cvt_pk_bf16_f32 v5, v8, v9
	v_mad_u64_u32 v[6:7], s[18:19], v30, s89, v[0:1]
	ds_write_b128 v6, v[2:5] offset:55296
.LBB0_488:
	s_or_b64 exec, exec, s[16:17]
	v_and_b32_e32 v10, 31, v42
	v_readlane_b32 s4, v253, 39
	s_lshl_b32 s11, s33, 7
	s_add_i32 s11, s11, s22
	v_or_b32_e32 v38, s4, v10
	v_add_u32_e32 v2, s11, v38
	v_ashrrev_i32_e32 v3, 31, v2
	v_lshl_add_u64 v[2:3], v[2:3], 2, s[64:65]
	s_waitcnt lgkmcnt(0)
	s_barrier
	v_add_u32_e32 v0, s44, v38
	v_mov_b64_e32 v[2:3], s[68:69]
	v_ashrrev_i32_e32 v11, 2, v42
	v_mad_u64_u32 v[2:3], s[16:17], v0, s73, v[2:3]
	v_readlane_b32 s4, v253, 40
	v_and_b32_e32 v34, -8, v11
	s_lshl_b32 s44, s4, 1
	v_lshl_add_u64 v[2:3], s[0:1], 1, v[2:3]
	v_ashrrev_i32_e32 v35, 31, v34
	v_lshl_add_u64 v[2:3], v[2:3], 0, s[44:45]
	v_lshl_add_u64 v[2:3], v[34:35], 1, v[2:3]
	s_mov_b64 s[4:5], 0x1400
	v_lshl_add_u64 v[4:5], v[2:3], 0, s[4:5]
	s_mov_b64 s[4:5], 0x2400
	v_lshl_add_u64 v[6:7], v[2:3], 0, s[4:5]
	s_movk_i32 s4, 0x1000
	v_add_co_u32_e32 v8, vcc, s4, v2
	s_movk_i32 s4, 0x2000
	s_nop 0
	v_addc_co_u32_e32 v9, vcc, 0, v3, vcc
	v_add_co_u32_e32 v2, vcc, s4, v2
	v_readlane_b32 s4, v254, 55
	s_nop 0
	v_addc_co_u32_e32 v3, vcc, 0, v3, vcc
	v_add_u32_e32 v132, s14, v38
	v_mov_b64_e32 v[134:135], s[68:69]
	v_mad_u64_u32 v[134:135], vcc, v132, s73, v[134:135]
	v_lshl_add_u64 v[134:135], s[0:1], 1, v[134:135]
	v_lshl_add_u64 v[134:135], v[134:135], 0, s[44:45]
	v_lshl_add_u64 v[134:135], v[34:35], 1, v[134:135]
	s_mov_b64 s[16:17], 0x1000
	v_lshl_add_u64 v[136:137], v[134:135], 0, s[16:17]
	s_mov_b64 s[16:17], 0x2000
	v_lshl_add_u64 v[138:139], v[134:135], 0, s[16:17]
	s_mov_b64 s[16:17], 0x1400
	v_lshl_add_u64 v[140:141], v[134:135], 0, s[16:17]
	s_mov_b64 s[16:17], 0x2400
	v_lshl_add_u64 v[142:143], v[134:135], 0, s[16:17]
	global_load_dwordx4 v[80:83], v[136:137], off offset:1024
	global_load_dwordx4 v[76:79], v[138:139], off offset:1024
	global_load_dwordx4 v[72:75], v[140:141], off offset:32
	global_load_dwordx4 v[68:71], v[142:143], off offset:32
	v_add_u32_e32 v132, s12, v38
	v_mov_b64_e32 v[134:135], s[68:69]
	v_mad_u64_u32 v[134:135], vcc, v132, s73, v[134:135]
	v_lshl_add_u64 v[134:135], s[0:1], 1, v[134:135]
	v_lshl_add_u64 v[134:135], v[134:135], 0, s[44:45]
	v_lshl_add_u64 v[134:135], v[34:35], 1, v[134:135]
	s_mov_b64 s[16:17], 0x1000
	v_lshl_add_u64 v[136:137], v[134:135], 0, s[16:17]
	s_mov_b64 s[16:17], 0x2000
	v_lshl_add_u64 v[138:139], v[134:135], 0, s[16:17]
	s_mov_b64 s[16:17], 0x1400
	v_lshl_add_u64 v[140:141], v[134:135], 0, s[16:17]
	s_mov_b64 s[16:17], 0x2400
	v_lshl_add_u64 v[142:143], v[134:135], 0, s[16:17]
	global_load_dwordx4 v[96:99], v[136:137], off offset:1024
	global_load_dwordx4 v[92:95], v[138:139], off offset:1024
	global_load_dwordx4 v[88:91], v[140:141], off offset:32
	global_load_dwordx4 v[84:87], v[142:143], off offset:32
	v_add_u32_e32 v132, s10, v38
	v_mov_b64_e32 v[134:135], s[68:69]
	v_mad_u64_u32 v[134:135], vcc, v132, s73, v[134:135]
	v_lshl_add_u64 v[134:135], s[0:1], 1, v[134:135]
	v_lshl_add_u64 v[134:135], v[134:135], 0, s[44:45]
	v_lshl_add_u64 v[134:135], v[34:35], 1, v[134:135]
	s_mov_b64 s[16:17], 0x1000
	v_lshl_add_u64 v[136:137], v[134:135], 0, s[16:17]
	s_mov_b64 s[16:17], 0x2000
	v_lshl_add_u64 v[138:139], v[134:135], 0, s[16:17]
	s_mov_b64 s[16:17], 0x1400
	v_lshl_add_u64 v[140:141], v[134:135], 0, s[16:17]
	s_mov_b64 s[16:17], 0x2400
	v_lshl_add_u64 v[142:143], v[134:135], 0, s[16:17]
	global_load_dwordx4 v[112:115], v[136:137], off offset:1024
	global_load_dwordx4 v[108:111], v[138:139], off offset:1024
	global_load_dwordx4 v[104:107], v[140:141], off offset:32
	global_load_dwordx4 v[100:103], v[142:143], off offset:32
	v_lshrrev_b32_e32 v4, 3, v11
	v_mul_u32_u24_e32 v3, 0x110, v10
	v_lshlrev_b32_e32 v5, 4, v4
	s_movk_i32 s11, 0x480
	v_bfe_u32 v2, v42, 2, 2
	v_add3_u32 v37, v3, v5, s4
	v_mul_lo_u32 v3, v4, s11
	v_mad_u32_u24 v2, v2, s89, v3
	v_lshlrev_b32_e32 v3, 1, v42
	v_and_b32_e32 v3, 32, v3
	v_lshlrev_b32_e32 v4, 3, v45
	v_add3_u32 v39, v2, v3, v4
	v_readlane_b32 s4, v254, 58
	v_mov_b32_e32 v2, 0
	v_mov_b32_e32 v41, v37
	v_add_u32_e32 v40, s4, v39
	s_mov_b32 s11, s77
	v_mov_b32_e32 v3, v2
	v_mov_b32_e32 v4, v2
	v_mov_b32_e32 v5, v2
	v_mov_b32_e32 v6, v2
	v_mov_b32_e32 v7, v2
	v_mov_b32_e32 v8, v2
	v_mov_b32_e32 v9, v2
	v_mov_b32_e32 v10, v2
	v_mov_b32_e32 v11, v2
	v_mov_b32_e32 v12, v2
	v_mov_b32_e32 v13, v2
	v_mov_b32_e32 v14, v2
	v_mov_b32_e32 v15, v2
	v_mov_b32_e32 v16, v2
	v_mov_b32_e32 v17, v2
	ds_read_b64_tr_b16 v[44:45], v40
	ds_read_b64_tr_b16 v[46:47], v40 offset:576
	ds_read_b128 v[48:51], v41

; __device__ __forceinline__ unsigned pk2(float lo, float hi) { const f32x2 v = {lo, hi}; return __builtin_bit_cast(unsigned, __builtin_convertvector(v, bf16x2_t)); }
; __device__ __forceinline__ void gmlp_task(LAS unsigned char* lds, const Params& p, const bf16_t* P, bf16_t* Y, const float* svg, float* ssb, int l, bool sample, int b, int g, int q, int tid, int wave, int lane, bool load_ws = true) {
;     ...
;             bf16_t* yp = Y + row * DM + 1024 + g * 64 + 32 * dt + 8 * h;
;             float ss = 0.f;
; #pragma unroll
;             for (int pr = 0; pr < 2; ++pr) {
;                 float a[4], bq[4];
; #pragma unroll
;                 for (int k = 0; k < 4; ++k) { a[k] = acc[8 * pr + k] + bias; bq[k] = acc[8 * pr + 4 + k] + bias; }
; #pragma unroll
;                 for (int k = 0; k < 4; ++k) swap_halves(a[k], bq[k]);
;                 const u32x4 u4 = uw[pr], g4 = gw[pr];
;                 a[0] *= bf_lo(u4.x); a[1] *= bf_hi(u4.x); a[2] *= bf_lo(u4.y); a[3] *= bf_hi(u4.y); bq[0] *= bf_lo(u4.z); bq[1] *= bf_hi(u4.z); bq[2] *= bf_lo(u4.w); bq[3] *= bf_hi(u4.w);
;                 ss += ((a[0] * a[0] + a[1] * a[1]) + (a[2] * a[2] + a[3] * a[3])) + ((bq[0] * bq[0] + bq[1] * bq[1]) + (bq[2] * bq[2] + bq[3] * bq[3]));
;                 u32x4 w; w.x = pk2(a[0] * bf_lo(g4.x), a[1] * bf_hi(g4.x)); w.y = pk2(a[2] * bf_lo(g4.y), a[3] * bf_hi(g4.y));
;                 w.z = pk2(bq[0] * bf_lo(g4.z), bq[1] * bf_hi(g4.z)); w.w = pk2(bq[2] * bf_lo(g4.w), bq[3] * bf_hi(g4.w));
;                 *(u32x4*)(yp + 16 * pr) = w;
;             }
;             ss += __shfl_xor(ss, 32);
;             if (h == 0) ssb[row * 32 + g * 2 + dt] = ss;
.Lmy_c489_tail:
	s_waitcnt lgkmcnt(0)
	v_mfma_f32_32x32x16_bf16 v[2:17], v[116:119], v[120:123], v[2:17]
	v_lshlrev_b64 v[40:41], 12, v[0:1]
	v_lshl_add_u64 v[40:41], s[36:37], 0, v[40:41]
	v_lshl_add_u64 v[40:41], s[0:1], 1, v[40:41]
	s_waitcnt vmcnt(16)
	s_nop 6
	v_add_f32_e32 v2, v168, v2
	v_add_f32_e32 v6, v168, v6
	v_add_f32_e32 v3, v168, v3
	v_add_f32_e32 v7, v168, v7
	v_add_f32_e32 v4, v168, v4
	v_add_f32_e32 v8, v168, v8
	v_add_f32_e32 v5, v168, v5
	v_add_f32_e32 v9, v168, v9
	v_lshl_add_u64 v[40:41], v[40:41], 0, s[44:45]
	v_permlane32_swap_b32_e32 v2, v6
	v_permlane32_swap_b32_e32 v3, v7
	v_permlane32_swap_b32_e32 v4, v8
	v_permlane32_swap_b32_e32 v5, v9
	v_cmp_gt_u32_e64 s[40:41], 32, v42
	v_lshl_add_u64 v[42:43], v[34:35], 1, v[40:41]
	s_waitcnt vmcnt(15)
	v_lshlrev_b32_e32 v40, 16, v164
	v_and_b32_e32 v41, 0xffff0000, v164
	v_lshlrev_b32_e32 v30, 16, v165
	v_and_b32_e32 v31, 0xffff0000, v165
	v_pk_mul_f32 v[2:3], v[40:41], v[2:3]
	s_waitcnt vmcnt(14)
	v_lshlrev_b32_e32 v44, 16, v160
	v_and_b32_e32 v45, 0xffff0000, v160
	v_pk_mul_f32 v[4:5], v[30:31], v[4:5]
	v_lshlrev_b32_e32 v26, 16, v161
	v_and_b32_e32 v27, 0xffff0000, v161
	v_pk_mul_f32 v[40:41], v[2:3], v[2:3]
	v_pk_mul_f32 v[2:3], v[2:3], v[44:45]
	v_pk_mul_f32 v[30:31], v[4:5], v[4:5]
	v_pk_mul_f32 v[4:5], v[4:5], v[26:27]
	v_cvt_pk_bf16_f32 v2, v2, v3
	v_cvt_pk_bf16_f32 v3, v4, v5
	v_lshlrev_b32_e32 v4, 16, v166
	v_and_b32_e32 v5, 0xffff0000, v166
	v_pk_mul_f32 v[4:5], v[4:5], v[6:7]
	v_lshlrev_b32_e32 v6, 16, v162
	v_and_b32_e32 v7, 0xffff0000, v162
	v_pk_mul_f32 v[26:27], v[4:5], v[4:5]
	v_pk_mul_f32 v[4:5], v[4:5], v[6:7]
	v_lshlrev_b32_e32 v6, 16, v167
	v_and_b32_e32 v7, 0xffff0000, v167
	v_pk_mul_f32 v[6:7], v[6:7], v[8:9]
	v_lshlrev_b32_e32 v28, 16, v163
	v_and_b32_e32 v29, 0xffff0000, v163
	v_pk_mul_f32 v[8:9], v[6:7], v[6:7]
	v_pk_mul_f32 v[6:7], v[6:7], v[28:29]
	v_cvt_pk_bf16_f32 v4, v4, v5
	v_cvt_pk_bf16_f32 v5, v6, v7
	global_store_dwordx4 v[42:43], v[2:5], off offset:2048
	v_add_f32_e32 v6, v168, v14
	v_add_f32_e32 v7, v168, v15
	v_add_f32_e32 v2, v168, v10
	v_add_f32_e32 v3, v168, v11
	s_nop 0
	v_permlane32_swap_b32_e32 v2, v6
	v_permlane32_swap_b32_e32 v3, v7
	s_waitcnt vmcnt(14)
	v_lshlrev_b32_e32 v4, 16, v156
	v_and_b32_e32 v5, 0xffff0000, v156
	v_pk_mul_f32 v[2:3], v[4:5], v[2:3]
	s_waitcnt vmcnt(13)
	v_lshlrev_b32_e32 v4, 16, v152
	v_and_b32_e32 v5, 0xffff0000, v152
	v_add_f32_e32 v10, v168, v12
	v_add_f32_e32 v12, v168, v16
	v_add_f32_e32 v11, v168, v13
	v_add_f32_e32 v13, v168, v17
	v_pk_mul_f32 v[14:15], v[2:3], v[2:3]
	v_pk_mul_f32 v[2:3], v[2:3], v[4:5]
	v_permlane32_swap_b32_e32 v10, v12
	v_permlane32_swap_b32_e32 v11, v13
	v_cvt_pk_bf16_f32 v4, v2, v3
	v_lshlrev_b32_e32 v2, 16, v157
	v_and_b32_e32 v3, 0xffff0000, v157
	v_lshlrev_b32_e32 v16, 16, v153
	v_pk_mul_f32 v[2:3], v[2:3], v[10:11]
	v_and_b32_e32 v17, 0xffff0000, v153
	v_pk_mul_f32 v[10:11], v[2:3], v[2:3]
	v_pk_mul_f32 v[2:3], v[2:3], v[16:17]
	s_lshl_b32 s16, s33, 1
	v_cvt_pk_bf16_f32 v5, v2, v3
	v_lshlrev_b32_e32 v2, 16, v158
	v_and_b32_e32 v3, 0xffff0000, v158
	v_pk_mul_f32 v[2:3], v[2:3], v[6:7]
	v_lshlrev_b32_e32 v6, 16, v154
	v_and_b32_e32 v7, 0xffff0000, v154
	v_pk_mul_f32 v[16:17], v[2:3], v[2:3]
	v_pk_mul_f32 v[2:3], v[2:3], v[6:7]
	v_add_f32_e32 v7, v8, v9
	v_cvt_pk_bf16_f32 v6, v2, v3
	v_lshlrev_b32_e32 v2, 16, v159
	v_and_b32_e32 v3, 0xffff0000, v159
	v_pk_mul_f32 v[12:13], v[2:3], v[12:13]
	v_add_f32_e32 v8, v26, v27
	v_pk_mul_f32 v[2:3], v[12:13], v[12:13]
	v_add_f32_e32 v7, v8, v7
	v_add_f32_e32 v8, v30, v31
	v_add_f32_e32 v9, v40, v41
	v_add_f32_e32 v8, v9, v8
	v_add_f32_e32 v2, v2, v3
	v_add_f32_e32 v3, v16, v17
	v_add_f32_e32 v7, v8, v7
	v_add_f32_e32 v2, v3, v2
	v_add_f32_e32 v3, v10, v11
	v_add_f32_e32 v8, v14, v15
	v_add_f32_e32 v3, v8, v3
	v_add_f32_e32 v2, v3, v2
	v_xor_b32_e32 v3, 32, v185
	v_cmp_lt_i32_e32 vcc, v3, v186
	v_add_f32_e32 v2, v7, v2
	s_ashr_i32 s17, s16, 31
	v_cndmask_b32_e32 v3, v185, v3, vcc
	v_lshlrev_b32_e32 v40, 2, v3
	ds_bpermute_b32 v3, v40, v2
	s_lshl_b64 s[16:17], s[16:17], 2
	v_readlane_b32 s4, v253, 41
	v_lshlrev_b32_e32 v8, 16, v155
	v_and_b32_e32 v9, 0xffff0000, v155
	s_add_u32 s16, s4, s16
	v_readlane_b32 s4, v253, 44
	v_pk_mul_f32 v[8:9], v[12:13], v[8:9]
	s_addc_u32 s17, s4, s17
	v_cvt_pk_bf16_f32 v7, v8, v9
	global_store_dwordx4 v[42:43], v[4:7], off offset:2080
	s_and_saveexec_b64 s[18:19], s[40:41]
	s_cbranch_execz .LBB0_492
	v_lshlrev_b64 v[4:5], 7, v[0:1]
	v_lshl_add_u64 v[4:5], s[16:17], 0, v[4:5]
	s_waitcnt lgkmcnt(0)
	v_add_f32_e32 v0, v2, v3
	global_store_dword v[4:5], v0, off

; __device__ __forceinline__ unsigned pk2(float lo, float hi) { const f32x2 v = {lo, hi}; return __builtin_bit_cast(unsigned, __builtin_convertvector(v, bf16x2_t)); }
; __device__ __forceinline__ void gmlp_task(LAS unsigned char* lds, const Params& p, const bf16_t* P, bf16_t* Y, const float* svg, float* ssb, int l, bool sample, int b, int g, int q, int tid, int wave, int lane, bool load_ws = true) {
;     ...
;             bf16_t* yp = Y + row * DM + 1024 + g * 64 + 32 * dt + 8 * h;
;             float ss = 0.f;
; #pragma unroll
;             for (int pr = 0; pr < 2; ++pr) {
;                 float a[4], bq[4];
; #pragma unroll
;                 for (int k = 0; k < 4; ++k) { a[k] = acc[8 * pr + k] + bias; bq[k] = acc[8 * pr + 4 + k] + bias; }
; #pragma unroll
;                 for (int k = 0; k < 4; ++k) swap_halves(a[k], bq[k]);
;                 const u32x4 u4 = uw[pr], g4 = gw[pr];
;                 a[0] *= bf_lo(u4.x); a[1] *= bf_hi(u4.x); a[2] *= bf_lo(u4.y); a[3] *= bf_hi(u4.y); bq[0] *= bf_lo(u4.z); bq[1] *= bf_hi(u4.z); bq[2] *= bf_lo(u4.w); bq[3] *= bf_hi(u4.w);
;                 ss += ((a[0] * a[0] + a[1] * a[1]) + (a[2] * a[2] + a[3] * a[3])) + ((bq[0] * bq[0] + bq[1] * bq[1]) + (bq[2] * bq[2] + bq[3] * bq[3]));
;                 u32x4 w; w.x = pk2(a[0] * bf_lo(g4.x), a[1] * bf_hi(g4.x)); w.y = pk2(a[2] * bf_lo(g4.y), a[3] * bf_hi(g4.y));
;                 w.z = pk2(bq[0] * bf_lo(g4.z), bq[1] * bf_hi(g4.z)); w.w = pk2(bq[2] * bf_lo(g4.w), bq[3] * bf_hi(g4.w));
;                 *(u32x4*)(yp + 16 * pr) = w;
;             }
;             ss += __shfl_xor(ss, 32);
;             if (h == 0) ssb[row * 32 + g * 2 + dt] = ss;
.Lmy_c493_tail:
	s_waitcnt lgkmcnt(0)
	v_mfma_f32_32x32x16_bf16 v[2:17], v[116:119], v[120:123], v[2:17]
	s_nop 10
	v_add_f32_e32 v2, v168, v2
	v_add_f32_e32 v6, v168, v6
	v_add_f32_e32 v3, v168, v3
	v_add_f32_e32 v7, v168, v7
	v_add_f32_e32 v4, v168, v4
	v_add_f32_e32 v8, v168, v8
	v_add_f32_e32 v5, v168, v5
	v_add_f32_e32 v9, v168, v9
	v_permlane32_swap_b32_e32 v2, v6
	v_permlane32_swap_b32_e32 v3, v7
	v_permlane32_swap_b32_e32 v4, v8
	v_permlane32_swap_b32_e32 v5, v9
	s_waitcnt vmcnt(14)
	v_lshlrev_b32_e32 v44, 16, v80
	v_and_b32_e32 v45, 0xffff0000, v80
	v_lshlrev_b32_e32 v30, 16, v81
	v_and_b32_e32 v31, 0xffff0000, v81
	v_pk_mul_f32 v[2:3], v[44:45], v[2:3]
	s_waitcnt vmcnt(13)
	v_lshlrev_b32_e32 v46, 16, v76
	v_and_b32_e32 v47, 0xffff0000, v76
	v_pk_mul_f32 v[4:5], v[30:31], v[4:5]
	v_lshlrev_b32_e32 v26, 16, v77
	v_and_b32_e32 v27, 0xffff0000, v77
	v_pk_mul_f32 v[44:45], v[2:3], v[2:3]
	v_pk_mul_f32 v[2:3], v[2:3], v[46:47]
	v_pk_mul_f32 v[30:31], v[4:5], v[4:5]
	v_pk_mul_f32 v[4:5], v[4:5], v[26:27]
	v_cvt_pk_bf16_f32 v2, v2, v3
	v_cvt_pk_bf16_f32 v3, v4, v5
	v_lshlrev_b32_e32 v4, 16, v82
	v_and_b32_e32 v5, 0xffff0000, v82
	v_lshlrev_b64 v[42:43], 12, v[0:1]
	v_pk_mul_f32 v[4:5], v[4:5], v[6:7]
	v_lshlrev_b32_e32 v6, 16, v78
	v_and_b32_e32 v7, 0xffff0000, v78
	v_lshl_add_u64 v[42:43], s[36:37], 0, v[42:43]
	v_pk_mul_f32 v[26:27], v[4:5], v[4:5]
	v_pk_mul_f32 v[4:5], v[4:5], v[6:7]
	v_lshlrev_b32_e32 v6, 16, v83
	v_and_b32_e32 v7, 0xffff0000, v83
	v_lshl_add_u64 v[42:43], s[0:1], 1, v[42:43]
	v_pk_mul_f32 v[6:7], v[6:7], v[8:9]
	v_lshlrev_b32_e32 v28, 16, v79
	v_and_b32_e32 v29, 0xffff0000, v79
	v_lshl_add_u64 v[42:43], v[42:43], 0, s[44:45]
	v_pk_mul_f32 v[8:9], v[6:7], v[6:7]
	v_pk_mul_f32 v[6:7], v[6:7], v[28:29]
	v_lshl_add_u64 v[42:43], v[34:35], 1, v[42:43]
	v_cvt_pk_bf16_f32 v4, v4, v5
	v_cvt_pk_bf16_f32 v5, v6, v7
	global_store_dwordx4 v[42:43], v[2:5], off offset:2048
	v_add_f32_e32 v6, v168, v14
	v_add_f32_e32 v7, v168, v15
	v_add_f32_e32 v2, v168, v10
	v_add_f32_e32 v3, v168, v11
	s_nop 0
	v_permlane32_swap_b32_e32 v2, v6
	v_permlane32_swap_b32_e32 v3, v7
	s_waitcnt vmcnt(13)
	v_lshlrev_b32_e32 v4, 16, v72
	v_and_b32_e32 v5, 0xffff0000, v72
	v_pk_mul_f32 v[2:3], v[4:5], v[2:3]
	s_waitcnt vmcnt(12)
	v_lshlrev_b32_e32 v4, 16, v68
	v_and_b32_e32 v5, 0xffff0000, v68
	v_add_f32_e32 v10, v168, v12
	v_add_f32_e32 v12, v168, v16
	v_add_f32_e32 v11, v168, v13
	v_add_f32_e32 v13, v168, v17
	v_pk_mul_f32 v[14:15], v[2:3], v[2:3]
	v_pk_mul_f32 v[2:3], v[2:3], v[4:5]
	v_permlane32_swap_b32_e32 v10, v12
	v_permlane32_swap_b32_e32 v11, v13
	v_cvt_pk_bf16_f32 v4, v2, v3
	v_lshlrev_b32_e32 v2, 16, v73
	v_and_b32_e32 v3, 0xffff0000, v73
	v_lshlrev_b32_e32 v16, 16, v69
	v_pk_mul_f32 v[2:3], v[2:3], v[10:11]
	v_and_b32_e32 v17, 0xffff0000, v69
	v_pk_mul_f32 v[10:11], v[2:3], v[2:3]
	v_pk_mul_f32 v[2:3], v[2:3], v[16:17]
	s_nop 0
	v_cvt_pk_bf16_f32 v5, v2, v3
	v_lshlrev_b32_e32 v2, 16, v74
	v_and_b32_e32 v3, 0xffff0000, v74
	v_pk_mul_f32 v[2:3], v[2:3], v[6:7]
	v_lshlrev_b32_e32 v6, 16, v70
	v_and_b32_e32 v7, 0xffff0000, v70
	v_pk_mul_f32 v[16:17], v[2:3], v[2:3]
	v_pk_mul_f32 v[2:3], v[2:3], v[6:7]
	v_add_f32_e32 v7, v8, v9
	v_cvt_pk_bf16_f32 v6, v2, v3
	v_lshlrev_b32_e32 v2, 16, v75
	v_and_b32_e32 v3, 0xffff0000, v75
	v_pk_mul_f32 v[12:13], v[2:3], v[12:13]
	v_add_f32_e32 v8, v26, v27
	v_pk_mul_f32 v[2:3], v[12:13], v[12:13]
	v_add_f32_e32 v7, v8, v7
	v_add_f32_e32 v8, v30, v31
	v_add_f32_e32 v9, v44, v45
	v_add_f32_e32 v8, v9, v8
	v_add_f32_e32 v2, v2, v3
	v_add_f32_e32 v3, v16, v17
	v_add_f32_e32 v7, v8, v7
	v_add_f32_e32 v2, v3, v2
	v_add_f32_e32 v3, v10, v11
	v_add_f32_e32 v8, v14, v15
	v_add_f32_e32 v3, v8, v3
	v_add_f32_e32 v2, v3, v2
	v_add_f32_e32 v2, v7, v2
	ds_bpermute_b32 v3, v40, v2
	v_lshlrev_b32_e32 v8, 16, v71
	v_and_b32_e32 v9, 0xffff0000, v71
	v_pk_mul_f32 v[8:9], v[12:13], v[8:9]
	s_nop 0
	v_cvt_pk_bf16_f32 v7, v8, v9
	global_store_dwordx4 v[42:43], v[4:7], off offset:2080
	s_and_saveexec_b64 s[14:15], s[40:41]
	s_cbranch_execz .LBB0_496
	v_lshlrev_b64 v[4:5], 7, v[0:1]
	v_lshl_add_u64 v[4:5], s[16:17], 0, v[4:5]
	s_waitcnt lgkmcnt(0)
	v_add_f32_e32 v0, v2, v3
	global_store_dword v[4:5], v0, off

; __device__ __forceinline__ unsigned pk2(float lo, float hi) { const f32x2 v = {lo, hi}; return __builtin_bit_cast(unsigned, __builtin_convertvector(v, bf16x2_t)); }
; __device__ __forceinline__ void gmlp_task(LAS unsigned char* lds, const Params& p, const bf16_t* P, bf16_t* Y, const float* svg, float* ssb, int l, bool sample, int b, int g, int q, int tid, int wave, int lane, bool load_ws = true) {
;     ...
;             bf16_t* yp = Y + row * DM + 1024 + g * 64 + 32 * dt + 8 * h;
;             float ss = 0.f;
; #pragma unroll
;             for (int pr = 0; pr < 2; ++pr) {
;                 float a[4], bq[4];
; #pragma unroll
;                 for (int k = 0; k < 4; ++k) { a[k] = acc[8 * pr + k] + bias; bq[k] = acc[8 * pr + 4 + k] + bias; }
; #pragma unroll
;                 for (int k = 0; k < 4; ++k) swap_halves(a[k], bq[k]);
;                 const u32x4 u4 = uw[pr], g4 = gw[pr];
;                 a[0] *= bf_lo(u4.x); a[1] *= bf_hi(u4.x); a[2] *= bf_lo(u4.y); a[3] *= bf_hi(u4.y); bq[0] *= bf_lo(u4.z); bq[1] *= bf_hi(u4.z); bq[2] *= bf_lo(u4.w); bq[3] *= bf_hi(u4.w);
;                 ss += ((a[0] * a[0] + a[1] * a[1]) + (a[2] * a[2] + a[3] * a[3])) + ((bq[0] * bq[0] + bq[1] * bq[1]) + (bq[2] * bq[2] + bq[3] * bq[3]));
;                 u32x4 w; w.x = pk2(a[0] * bf_lo(g4.x), a[1] * bf_hi(g4.x)); w.y = pk2(a[2] * bf_lo(g4.y), a[3] * bf_hi(g4.y));
;                 w.z = pk2(bq[0] * bf_lo(g4.z), bq[1] * bf_hi(g4.z)); w.w = pk2(bq[2] * bf_lo(g4.w), bq[3] * bf_hi(g4.w));
;                 *(u32x4*)(yp + 16 * pr) = w;
;             }
;             ss += __shfl_xor(ss, 32);
;             if (h == 0) ssb[row * 32 + g * 2 + dt] = ss;
.Lmy_c497_tail:
	s_waitcnt lgkmcnt(0)
	v_mfma_f32_32x32x16_bf16 v[2:17], v[116:119], v[120:123], v[2:17]
	s_nop 10
	v_add_f32_e32 v2, v168, v2
	v_add_f32_e32 v6, v168, v6
	v_add_f32_e32 v3, v168, v3
	v_add_f32_e32 v7, v168, v7
	v_add_f32_e32 v4, v168, v4
	v_add_f32_e32 v8, v168, v8
	v_add_f32_e32 v5, v168, v5
	v_add_f32_e32 v9, v168, v9
	v_permlane32_swap_b32_e32 v2, v6
	v_permlane32_swap_b32_e32 v3, v7
	v_permlane32_swap_b32_e32 v4, v8
	v_permlane32_swap_b32_e32 v5, v9
	s_waitcnt vmcnt(13)
	v_lshlrev_b32_e32 v44, 16, v96
	v_and_b32_e32 v45, 0xffff0000, v96
	v_lshlrev_b32_e32 v30, 16, v97
	v_and_b32_e32 v31, 0xffff0000, v97
	v_pk_mul_f32 v[2:3], v[44:45], v[2:3]
	s_waitcnt vmcnt(12)
	v_lshlrev_b32_e32 v46, 16, v92
	v_and_b32_e32 v47, 0xffff0000, v92
	v_pk_mul_f32 v[4:5], v[30:31], v[4:5]
	v_lshlrev_b32_e32 v26, 16, v93
	v_and_b32_e32 v27, 0xffff0000, v93
	v_pk_mul_f32 v[44:45], v[2:3], v[2:3]
	v_pk_mul_f32 v[2:3], v[2:3], v[46:47]
	v_pk_mul_f32 v[30:31], v[4:5], v[4:5]
	v_pk_mul_f32 v[4:5], v[4:5], v[26:27]
	v_cvt_pk_bf16_f32 v2, v2, v3
	v_cvt_pk_bf16_f32 v3, v4, v5
	v_lshlrev_b32_e32 v4, 16, v98
	v_and_b32_e32 v5, 0xffff0000, v98
	v_lshlrev_b64 v[42:43], 12, v[0:1]
	v_pk_mul_f32 v[4:5], v[4:5], v[6:7]
	v_lshlrev_b32_e32 v6, 16, v94
	v_and_b32_e32 v7, 0xffff0000, v94
	v_lshl_add_u64 v[42:43], s[36:37], 0, v[42:43]
	v_pk_mul_f32 v[26:27], v[4:5], v[4:5]
	v_pk_mul_f32 v[4:5], v[4:5], v[6:7]
	v_lshlrev_b32_e32 v6, 16, v99
	v_and_b32_e32 v7, 0xffff0000, v99
	v_lshl_add_u64 v[42:43], s[0:1], 1, v[42:43]
	v_pk_mul_f32 v[6:7], v[6:7], v[8:9]
	v_lshlrev_b32_e32 v28, 16, v95
	v_and_b32_e32 v29, 0xffff0000, v95
	v_lshl_add_u64 v[42:43], v[42:43], 0, s[44:45]
	v_pk_mul_f32 v[8:9], v[6:7], v[6:7]
	v_pk_mul_f32 v[6:7], v[6:7], v[28:29]
	v_lshl_add_u64 v[42:43], v[34:35], 1, v[42:43]
	v_cvt_pk_bf16_f32 v4, v4, v5
	v_cvt_pk_bf16_f32 v5, v6, v7
	global_store_dwordx4 v[42:43], v[2:5], off offset:2048
	v_add_f32_e32 v6, v168, v14
	v_add_f32_e32 v7, v168, v15
	v_add_f32_e32 v2, v168, v10
	v_add_f32_e32 v3, v168, v11
	s_nop 0
	v_permlane32_swap_b32_e32 v2, v6
	v_permlane32_swap_b32_e32 v3, v7
	s_waitcnt vmcnt(12)
	v_lshlrev_b32_e32 v4, 16, v88
	v_and_b32_e32 v5, 0xffff0000, v88
	v_pk_mul_f32 v[2:3], v[4:5], v[2:3]
	s_waitcnt vmcnt(11)
	v_lshlrev_b32_e32 v4, 16, v84
	v_and_b32_e32 v5, 0xffff0000, v84
	v_add_f32_e32 v10, v168, v12
	v_add_f32_e32 v12, v168, v16
	v_add_f32_e32 v11, v168, v13
	v_add_f32_e32 v13, v168, v17
	v_pk_mul_f32 v[14:15], v[2:3], v[2:3]
	v_pk_mul_f32 v[2:3], v[2:3], v[4:5]
	v_permlane32_swap_b32_e32 v10, v12
	v_permlane32_swap_b32_e32 v11, v13
	v_cvt_pk_bf16_f32 v4, v2, v3
	v_lshlrev_b32_e32 v2, 16, v89
	v_and_b32_e32 v3, 0xffff0000, v89
	v_lshlrev_b32_e32 v16, 16, v85
	v_pk_mul_f32 v[2:3], v[2:3], v[10:11]
	v_and_b32_e32 v17, 0xffff0000, v85
	v_pk_mul_f32 v[10:11], v[2:3], v[2:3]
	v_pk_mul_f32 v[2:3], v[2:3], v[16:17]
	s_nop 0
	v_cvt_pk_bf16_f32 v5, v2, v3
	v_lshlrev_b32_e32 v2, 16, v90
	v_and_b32_e32 v3, 0xffff0000, v90
	v_pk_mul_f32 v[2:3], v[2:3], v[6:7]
	v_lshlrev_b32_e32 v6, 16, v86
	v_and_b32_e32 v7, 0xffff0000, v86
	v_pk_mul_f32 v[16:17], v[2:3], v[2:3]
	v_pk_mul_f32 v[2:3], v[2:3], v[6:7]
	v_add_f32_e32 v7, v8, v9
	v_cvt_pk_bf16_f32 v6, v2, v3
	v_lshlrev_b32_e32 v2, 16, v91
	v_and_b32_e32 v3, 0xffff0000, v91
	v_pk_mul_f32 v[12:13], v[2:3], v[12:13]
	v_add_f32_e32 v8, v26, v27
	v_pk_mul_f32 v[2:3], v[12:13], v[12:13]
	v_add_f32_e32 v7, v8, v7
	v_add_f32_e32 v8, v30, v31
	v_add_f32_e32 v9, v44, v45
	v_add_f32_e32 v8, v9, v8
	v_add_f32_e32 v2, v2, v3
	v_add_f32_e32 v3, v16, v17
	v_add_f32_e32 v7, v8, v7
	v_add_f32_e32 v2, v3, v2
	v_add_f32_e32 v3, v10, v11
	v_add_f32_e32 v8, v14, v15
	v_add_f32_e32 v3, v8, v3
	v_add_f32_e32 v2, v3, v2
	v_add_f32_e32 v2, v7, v2
	ds_bpermute_b32 v3, v40, v2
	v_lshlrev_b32_e32 v8, 16, v87
	v_and_b32_e32 v9, 0xffff0000, v87
	v_pk_mul_f32 v[8:9], v[12:13], v[8:9]
	s_nop 0
	v_cvt_pk_bf16_f32 v7, v8, v9
	global_store_dwordx4 v[42:43], v[4:7], off offset:2080
	s_and_saveexec_b64 s[12:13], s[40:41]
	s_cbranch_execz .LBB0_500
	v_lshlrev_b64 v[4:5], 7, v[0:1]
	v_lshl_add_u64 v[4:5], s[16:17], 0, v[4:5]
	s_waitcnt lgkmcnt(0)
	v_add_f32_e32 v0, v2, v3
	global_store_dword v[4:5], v0, off

; #define LAS __attribute__((address_space(3)))
; __device__ __forceinline__ void gmlp_task(LAS unsigned char* lds, const Params& p, const bf16_t* P, bf16_t* Y, const float* svg, float* ssb, int l, bool sample, int b, int g, int q, int tid, int wave, int lane, bool load_ws = true) {
;     ...
;             const int ch = id & 7, j = id >> 3;
;             const f32x2 mr = MUR[sub * 128 + j];
;             const float mean = mr.x, rstd = mr.y;
;             const u32x4 w = wraw[sub][k];
;             const f32x4 g0 = *(const f32x4*)(lg + ch * 8), g1 = *(const f32x4*)(lg + ch * 8 + 4), b0 = *(const f32x4*)(lb + ch * 8), b1 = *(const f32x4*)(lb + ch * 8 + 4);
;             f32x4 v0 = (f32x4){bf_lo(w.x), bf_hi(w.x), bf_lo(w.y), bf_hi(w.y)}, v1 = (f32x4){bf_lo(w.z), bf_hi(w.z), bf_lo(w.w), bf_hi(w.w)};
;             v0 = (v0 - mean) * rstd * g0 + b0; v1 = (v1 - mean) * rstd * g1 + b1;
;             if (sample) { float* dst = p.out + OUT_VGS + ((((size_t)l * 32 + cidx) * 32 + j) * 16 + g) * 64 + ch * 8; *(f32x4*)dst = v0; *(f32x4*)(dst + 4) = v1; }
;             *(LAS u32x4*)(VGT + j * 72 + ch * 8) = pack8(v0, v1);
;     ...
;             bf16_t* yp = Y + row * DM + 1024 + g * 64 + 32 * dt + 8 * h;
;             float ss = 0.f;
; #pragma unroll
;             for (int pr = 0; pr < 2; ++pr) {
;                 float a[4], bq[4];
; #pragma unroll
;                 for (int k = 0; k < 4; ++k) { a[k] = acc[8 * pr + k] + bias; bq[k] = acc[8 * pr + 4 + k] + bias; }
; #pragma unroll
;                 for (int k = 0; k < 4; ++k) swap_halves(a[k], bq[k]);
;                 const u32x4 u4 = uw[pr], g4 = gw[pr];
;                 a[0] *= bf_lo(u4.x); a[1] *= bf_hi(u4.x); a[2] *= bf_lo(u4.y); a[3] *= bf_hi(u4.y); bq[0] *= bf_lo(u4.z); bq[1] *= bf_hi(u4.z); bq[2] *= bf_lo(u4.w); bq[3] *= bf_hi(u4.w);
;                 ss += ((a[0] * a[0] + a[1] * a[1]) + (a[2] * a[2] + a[3] * a[3])) + ((bq[0] * bq[0] + bq[1] * bq[1]) + (bq[2] * bq[2] + bq[3] * bq[3]));
;                 u32x4 w; w.x = pk2(a[0] * bf_lo(g4.x), a[1] * bf_hi(g4.x)); w.y = pk2(a[2] * bf_lo(g4.y), a[3] * bf_hi(g4.y));
;                 w.z = pk2(bq[0] * bf_lo(g4.z), bq[1] * bf_hi(g4.z)); w.w = pk2(bq[2] * bf_lo(g4.w), bq[3] * bf_hi(g4.w));
;                 *(u32x4*)(yp + 16 * pr) = w;
;             }
;             ss += __shfl_xor(ss, 32);
;             if (h == 0) ssb[row * 32 + g * 2 + dt] = ss;
.Lmy_c501_tail:
	s_waitcnt lgkmcnt(0)
	v_mfma_f32_32x32x16_bf16 v[2:17], v[116:119], v[120:123], v[2:17]
	v_lshlrev_b64 v[38:39], 12, v[0:1]
	v_lshl_add_u64 v[38:39], s[36:37], 0, v[38:39]
	v_lshl_add_u64 v[38:39], s[0:1], 1, v[38:39]
	s_nop 7
	v_add_f32_e32 v2, v168, v2
	v_add_f32_e32 v6, v168, v6
	v_add_f32_e32 v3, v168, v3
	v_add_f32_e32 v7, v168, v7
	v_add_f32_e32 v4, v168, v4
	v_add_f32_e32 v8, v168, v8
	v_add_f32_e32 v5, v168, v5
	v_add_f32_e32 v9, v168, v9
	v_lshl_add_u64 v[38:39], v[38:39], 0, s[44:45]
	v_permlane32_swap_b32_e32 v2, v6
	v_permlane32_swap_b32_e32 v3, v7
	v_permlane32_swap_b32_e32 v4, v8
	v_permlane32_swap_b32_e32 v5, v9
	v_lshl_add_u64 v[34:35], v[34:35], 1, v[38:39]
	s_waitcnt vmcnt(12)
	v_lshlrev_b32_e32 v38, 16, v112
	v_and_b32_e32 v39, 0xffff0000, v112
	v_lshlrev_b32_e32 v30, 16, v113
	v_and_b32_e32 v31, 0xffff0000, v113
	v_pk_mul_f32 v[2:3], v[38:39], v[2:3]
	s_waitcnt vmcnt(11)
	v_lshlrev_b32_e32 v42, 16, v108
	v_and_b32_e32 v43, 0xffff0000, v108
	v_pk_mul_f32 v[4:5], v[30:31], v[4:5]
	v_lshlrev_b32_e32 v26, 16, v109
	v_and_b32_e32 v27, 0xffff0000, v109
	v_pk_mul_f32 v[38:39], v[2:3], v[2:3]
	v_pk_mul_f32 v[2:3], v[2:3], v[42:43]
	v_pk_mul_f32 v[30:31], v[4:5], v[4:5]
	v_pk_mul_f32 v[4:5], v[4:5], v[26:27]
	v_cvt_pk_bf16_f32 v2, v2, v3
	v_cvt_pk_bf16_f32 v3, v4, v5
	v_lshlrev_b32_e32 v4, 16, v114
	v_and_b32_e32 v5, 0xffff0000, v114
	v_pk_mul_f32 v[4:5], v[4:5], v[6:7]
	v_lshlrev_b32_e32 v6, 16, v110
	v_and_b32_e32 v7, 0xffff0000, v110
	v_pk_mul_f32 v[26:27], v[4:5], v[4:5]
	v_pk_mul_f32 v[4:5], v[4:5], v[6:7]
	v_lshlrev_b32_e32 v6, 16, v115
	v_and_b32_e32 v7, 0xffff0000, v115
	v_pk_mul_f32 v[6:7], v[6:7], v[8:9]
	v_lshlrev_b32_e32 v28, 16, v111
	v_and_b32_e32 v29, 0xffff0000, v111
	v_pk_mul_f32 v[8:9], v[6:7], v[6:7]
	v_pk_mul_f32 v[6:7], v[6:7], v[28:29]
	v_cvt_pk_bf16_f32 v4, v4, v5
	v_cvt_pk_bf16_f32 v5, v6, v7
	global_store_dwordx4 v[34:35], v[2:5], off offset:2048
	v_add_f32_e32 v6, v168, v14
	v_add_f32_e32 v7, v168, v15
	v_add_f32_e32 v2, v168, v10
	v_add_f32_e32 v3, v168, v11
	s_nop 0
	v_permlane32_swap_b32_e32 v2, v6
	v_permlane32_swap_b32_e32 v3, v7
	s_waitcnt vmcnt(11)
	v_lshlrev_b32_e32 v4, 16, v104
	v_and_b32_e32 v5, 0xffff0000, v104
	v_pk_mul_f32 v[2:3], v[4:5], v[2:3]
	s_waitcnt vmcnt(10)
	v_lshlrev_b32_e32 v4, 16, v100
	v_and_b32_e32 v5, 0xffff0000, v100
	v_add_f32_e32 v10, v168, v12
	v_add_f32_e32 v12, v168, v16
	v_add_f32_e32 v11, v168, v13
	v_add_f32_e32 v13, v168, v17
	v_pk_mul_f32 v[14:15], v[2:3], v[2:3]
	v_pk_mul_f32 v[2:3], v[2:3], v[4:5]
	v_permlane32_swap_b32_e32 v10, v12
	v_permlane32_swap_b32_e32 v11, v13
	v_cvt_pk_bf16_f32 v4, v2, v3
	v_lshlrev_b32_e32 v2, 16, v105
	v_and_b32_e32 v3, 0xffff0000, v105
	v_lshlrev_b32_e32 v16, 16, v101
	v_pk_mul_f32 v[2:3], v[2:3], v[10:11]
	v_and_b32_e32 v17, 0xffff0000, v101
	v_pk_mul_f32 v[10:11], v[2:3], v[2:3]
	v_pk_mul_f32 v[2:3], v[2:3], v[16:17]
	s_nop 0
	v_cvt_pk_bf16_f32 v5, v2, v3
	v_lshlrev_b32_e32 v2, 16, v106
	v_and_b32_e32 v3, 0xffff0000, v106
	v_pk_mul_f32 v[2:3], v[2:3], v[6:7]
	v_lshlrev_b32_e32 v6, 16, v102
	v_and_b32_e32 v7, 0xffff0000, v102
	v_pk_mul_f32 v[16:17], v[2:3], v[2:3]
	v_pk_mul_f32 v[2:3], v[2:3], v[6:7]
	v_add_f32_e32 v7, v8, v9
	v_cvt_pk_bf16_f32 v6, v2, v3
	v_lshlrev_b32_e32 v2, 16, v107
	v_and_b32_e32 v3, 0xffff0000, v107
	v_pk_mul_f32 v[12:13], v[2:3], v[12:13]
	v_add_f32_e32 v8, v26, v27
	v_pk_mul_f32 v[2:3], v[12:13], v[12:13]
	v_add_f32_e32 v7, v8, v7
	v_add_f32_e32 v8, v30, v31
	v_add_f32_e32 v9, v38, v39
	v_add_f32_e32 v8, v9, v8
	v_add_f32_e32 v2, v2, v3
	v_add_f32_e32 v3, v16, v17
	v_add_f32_e32 v7, v8, v7
	v_add_f32_e32 v2, v3, v2
	v_add_f32_e32 v3, v10, v11
	v_add_f32_e32 v8, v14, v15
	v_add_f32_e32 v3, v8, v3
	v_add_f32_e32 v2, v3, v2
	v_add_f32_e32 v2, v7, v2
	ds_bpermute_b32 v3, v40, v2
	v_lshlrev_b32_e32 v8, 16, v103
	v_and_b32_e32 v9, 0xffff0000, v103
	v_pk_mul_f32 v[8:9], v[12:13], v[8:9]
	s_nop 0
	v_cvt_pk_bf16_f32 v7, v8, v9
	global_store_dwordx4 v[34:35], v[4:7], off offset:2080
	s_and_saveexec_b64 s[0:1], s[40:41]
	s_cbranch_execz .LBB0_448
	v_lshlrev_b64 v[4:5], 7, v[0:1]
	v_lshl_add_u64 v[4:5], s[16:17], 0, v[4:5]
	s_waitcnt lgkmcnt(0)
	v_add_f32_e32 v0, v2, v3
	global_store_dword v[4:5], v0, off
	s_branch .LBB0_448
.LBB0_504:
	v_add_u32_e32 v32, 0x1a800, v31
	ds_read_b64 v[32:33], v32
	v_lshlrev_b32_e32 v40, 16, v26
	v_and_b32_e32 v41, 0xffff0000, v26
	v_lshlrev_b32_e32 v26, 16, v27
	v_and_b32_e32 v27, 0xffff0000, v27
	v_lshlrev_b32_e32 v43, 16, v28
	v_and_b32_e32 v44, 0xffff0000, v28
	v_lshlrev_b32_e32 v62, 16, v29
	v_and_b32_e32 v63, 0xffff0000, v29
	s_waitcnt lgkmcnt(0)
	v_sub_f32_e32 v27, v27, v32
	v_sub_f32_e32 v26, v26, v32
	v_sub_f32_e32 v29, v41, v32
	v_sub_f32_e32 v28, v40, v32
	v_pk_mul_f32 v[28:29], v[32:33], v[28:29] op_sel:[1,0]
	v_pk_mul_f32 v[26:27], v[32:33], v[26:27] op_sel:[1,0]
	s_waitcnt vmcnt(5)
	v_pk_fma_f32 v[40:41], v[198:199], v[26:27], v[206:207]
	v_pk_fma_f32 v[26:27], v[196:197], v[28:29], v[204:205]
	v_sub_f32_e32 v29, v63, v32
	v_sub_f32_e32 v28, v62, v32
	v_sub_f32_e32 v51, v44, v32
	v_sub_f32_e32 v50, v43, v32
	v_pk_mul_f32 v[50:51], v[32:33], v[50:51] op_sel:[1,0]
	v_pk_mul_f32 v[28:29], v[32:33], v[28:29] op_sel:[1,0]
	v_cvt_pk_bf16_f32 v26, v26, v27
	v_pk_fma_f32 v[32:33], v[194:195], v[28:29], v[202:203]
	v_pk_fma_f32 v[28:29], v[192:193], v[50:51], v[200:201]
	v_cvt_pk_bf16_f32 v27, v40, v41
	v_cvt_pk_bf16_f32 v28, v28, v29
	v_cvt_pk_bf16_f32 v29, v32, v33
	v_mad_u64_u32 v[32:33], s[18:19], v30, s89, v[0:1]
	ds_write_b128 v32, v[26:29]
	s_or_b64 exec, exec, s[16:17]
	s_and_saveexec_b64 s[16:17], s[42:43]
	s_cbranch_execz .LBB0_482
; #define LAS __attribute__((address_space(3)))
; __device__ __forceinline__ u32x4 pack8(f32x4 a, f32x4 b) { u32x4 w; w.x = pk2(a[0], a[1]); w.y = pk2(a[2], a[3]); w.z = pk2(b[0], b[1]); w.w = pk2(b[2], b[3]); return w; }
; __device__ __forceinline__ void gmlp_task(LAS unsigned char* lds, const Params& p, const bf16_t* P, bf16_t* Y, const float* svg, float* ssb, int l, bool sample, int b, int g, int q, int tid, int wave, int lane, bool load_ws = true) {
;     ...
; #pragma unroll
;         for (int k = 0; k < 2; ++k) {
;             const int id = tid + 512 * k;
;             if (id >= L * 8) continue;
;             const int ch = id & 7, j = id >> 3;
;             const f32x2 mr = MUR[sub * 128 + j];
;             const float mean = mr.x, rstd = mr.y;
;             const u32x4 w = wraw[sub][k];
;             const f32x4 g0 = *(const f32x4*)(lg + ch * 8), g1 = *(const f32x4*)(lg + ch * 8 + 4), b0 = *(const f32x4*)(lb + ch * 8), b1 = *(const f32x4*)(lb + ch * 8 + 4);
;             f32x4 v0 = (f32x4){bf_lo(w.x), bf_hi(w.x), bf_lo(w.y), bf_hi(w.y)}, v1 = (f32x4){bf_lo(w.z), bf_hi(w.z), bf_lo(w.w), bf_hi(w.w)};
;             v0 = (v0 - mean) * rstd * g0 + b0; v1 = (v1 - mean) * rstd * g1 + b1;
;             if (sample) { float* dst = p.out + OUT_VGS + ((((size_t)l * 32 + cidx) * 32 + j) * 16 + g) * 64 + ch * 8; *(f32x4*)dst = v0; *(f32x4*)(dst + 4) = v1; }
;             *(LAS u32x4*)(VGT + j * 72 + ch * 8) = pack8(v0, v1);
;         }
.LBB0_505:
	v_add_u32_e32 v26, 0x1ac00, v39
	ds_read_b64 v[32:33], v26
	v_lshlrev_b32_e32 v40, 16, v22
	v_and_b32_e32 v41, 0xffff0000, v22
	v_lshlrev_b32_e32 v22, 16, v23
	v_and_b32_e32 v23, 0xffff0000, v23
	v_lshlrev_b32_e32 v43, 16, v24
	v_and_b32_e32 v44, 0xffff0000, v24
	v_lshlrev_b32_e32 v58, 16, v25
	v_and_b32_e32 v59, 0xffff0000, v25
	s_waitcnt lgkmcnt(0)
	v_sub_f32_e32 v23, v23, v32
	v_sub_f32_e32 v22, v22, v32
	v_sub_f32_e32 v25, v41, v32
	v_sub_f32_e32 v24, v40, v32
	v_pk_mul_f32 v[24:25], v[32:33], v[24:25] op_sel:[1,0]
	v_pk_mul_f32 v[22:23], v[32:33], v[22:23] op_sel:[1,0]
	s_waitcnt vmcnt(5)
	v_pk_fma_f32 v[40:41], v[198:199], v[22:23], v[206:207]
	v_pk_fma_f32 v[22:23], v[196:197], v[24:25], v[204:205]
	v_sub_f32_e32 v25, v59, v32
	v_sub_f32_e32 v24, v58, v32
	v_sub_f32_e32 v47, v44, v32
	v_sub_f32_e32 v46, v43, v32
	v_pk_mul_f32 v[46:47], v[32:33], v[46:47] op_sel:[1,0]
	v_pk_mul_f32 v[24:25], v[32:33], v[24:25] op_sel:[1,0]
	v_cvt_pk_bf16_f32 v22, v22, v23
	v_pk_fma_f32 v[28:29], v[194:195], v[24:25], v[202:203]
	v_pk_fma_f32 v[24:25], v[192:193], v[46:47], v[200:201]
	v_cvt_pk_bf16_f32 v23, v40, v41
	v_cvt_pk_bf16_f32 v24, v24, v25
	v_cvt_pk_bf16_f32 v25, v28, v29
	v_mad_u64_u32 v[26:27], s[18:19], v38, s89, v[0:1]
	ds_write_b128 v26, v[22:25] offset:18432
	s_or_b64 exec, exec, s[16:17]
	s_and_saveexec_b64 s[16:17], s[40:41]
	s_cbranch_execz .LBB0_483
.LBB0_506:
	v_add_u32_e32 v22, 0x1ac00, v31
	ds_read_b64 v[32:33], v22
	v_lshlrev_b32_e32 v40, 16, v18
	v_and_b32_e32 v41, 0xffff0000, v18
	v_lshlrev_b32_e32 v18, 16, v19
	v_and_b32_e32 v19, 0xffff0000, v19
	v_lshlrev_b32_e32 v43, 16, v20
	v_and_b32_e32 v44, 0xffff0000, v20
	v_lshlrev_b32_e32 v54, 16, v21
	v_and_b32_e32 v55, 0xffff0000, v21
	s_waitcnt lgkmcnt(0)
	v_sub_f32_e32 v19, v19, v32
	v_sub_f32_e32 v18, v18, v32
	v_sub_f32_e32 v21, v41, v32
	v_sub_f32_e32 v20, v40, v32
	v_pk_mul_f32 v[20:21], v[32:33], v[20:21] op_sel:[1,0]
	v_pk_mul_f32 v[18:19], v[32:33], v[18:19] op_sel:[1,0]
	s_waitcnt vmcnt(5)
	v_pk_fma_f32 v[28:29], v[198:199], v[18:19], v[206:207]
	v_pk_fma_f32 v[18:19], v[196:197], v[20:21], v[204:205]
	v_sub_f32_e32 v21, v55, v32
	v_sub_f32_e32 v20, v54, v32
	v_sub_f32_e32 v27, v44, v32
	v_sub_f32_e32 v26, v43, v32
	v_pk_mul_f32 v[26:27], v[32:33], v[26:27] op_sel:[1,0]
	v_pk_mul_f32 v[20:21], v[32:33], v[20:21] op_sel:[1,0]
	v_cvt_pk_bf16_f32 v18, v18, v19
	v_pk_fma_f32 v[24:25], v[194:195], v[20:21], v[202:203]
	v_pk_fma_f32 v[20:21], v[192:193], v[26:27], v[200:201]
	v_cvt_pk_bf16_f32 v19, v28, v29
	v_cvt_pk_bf16_f32 v20, v20, v21
	v_cvt_pk_bf16_f32 v21, v24, v25
	v_mad_u64_u32 v[22:23], s[18:19], v30, s89, v[0:1]
	ds_write_b128 v22, v[18:21] offset:18432
	s_or_b64 exec, exec, s[16:17]
	s_and_saveexec_b64 s[16:17], s[42:43]
	s_cbranch_execz .LBB0_484
.LBB0_507:
	v_add_u32_e32 v18, 0x1b000, v39
	ds_read_b64 v[32:33], v18
	v_lshlrev_b32_e32 v40, 16, v14
	v_and_b32_e32 v41, 0xffff0000, v14
	v_lshlrev_b32_e32 v14, 16, v15
	v_and_b32_e32 v15, 0xffff0000, v15
	v_lshlrev_b32_e32 v43, 16, v16
	v_and_b32_e32 v44, 0xffff0000, v16
	v_lshlrev_b32_e32 v50, 16, v17
	v_and_b32_e32 v51, 0xffff0000, v17
	s_waitcnt lgkmcnt(0)
	v_sub_f32_e32 v15, v15, v32
	v_sub_f32_e32 v14, v14, v32
	v_sub_f32_e32 v17, v41, v32
	v_sub_f32_e32 v16, v40, v32
	v_pk_mul_f32 v[16:17], v[32:33], v[16:17] op_sel:[1,0]
	v_pk_mul_f32 v[14:15], v[32:33], v[14:15] op_sel:[1,0]
	s_waitcnt vmcnt(5)
	v_pk_fma_f32 v[24:25], v[198:199], v[14:15], v[206:207]
	v_pk_fma_f32 v[14:15], v[196:197], v[16:17], v[204:205]
	v_sub_f32_e32 v17, v51, v32
	v_sub_f32_e32 v16, v50, v32
	v_sub_f32_e32 v23, v44, v32
	v_sub_f32_e32 v22, v43, v32
	v_pk_mul_f32 v[22:23], v[32:33], v[22:23] op_sel:[1,0]
	v_pk_mul_f32 v[16:17], v[32:33], v[16:17] op_sel:[1,0]
	v_cvt_pk_bf16_f32 v14, v14, v15
	v_pk_fma_f32 v[20:21], v[194:195], v[16:17], v[202:203]
	v_pk_fma_f32 v[16:17], v[192:193], v[22:23], v[200:201]
	v_cvt_pk_bf16_f32 v15, v24, v25
	v_cvt_pk_bf16_f32 v16, v16, v17
	v_cvt_pk_bf16_f32 v17, v20, v21
	v_mad_u64_u32 v[18:19], s[18:19], v38, s89, v[0:1]
	ds_write_b128 v18, v[14:17] offset:36864
	s_or_b64 exec, exec, s[16:17]
	s_and_saveexec_b64 s[16:17], s[40:41]
	s_cbranch_execz .LBB0_485
.LBB0_508:
	v_add_u32_e32 v14, 0x1b000, v31
	ds_read_b64 v[32:33], v14
	v_lshlrev_b32_e32 v40, 16, v10
	v_and_b32_e32 v41, 0xffff0000, v10
	v_lshlrev_b32_e32 v10, 16, v11
	v_and_b32_e32 v11, 0xffff0000, v11
	v_lshlrev_b32_e32 v43, 16, v12
	v_and_b32_e32 v44, 0xffff0000, v12
	v_lshlrev_b32_e32 v46, 16, v13
	v_and_b32_e32 v47, 0xffff0000, v13
	s_waitcnt lgkmcnt(0)
	v_sub_f32_e32 v11, v11, v32
	v_sub_f32_e32 v10, v10, v32
	v_sub_f32_e32 v13, v41, v32
	v_sub_f32_e32 v12, v40, v32
	v_pk_mul_f32 v[12:13], v[32:33], v[12:13] op_sel:[1,0]
	v_pk_mul_f32 v[10:11], v[32:33], v[10:11] op_sel:[1,0]
	s_waitcnt vmcnt(5)
	v_pk_fma_f32 v[20:21], v[198:199], v[10:11], v[206:207]
	v_pk_fma_f32 v[10:11], v[196:197], v[12:13], v[204:205]
	v_sub_f32_e32 v13, v47, v32
	v_sub_f32_e32 v12, v46, v32
	v_sub_f32_e32 v19, v44, v32
	v_sub_f32_e32 v18, v43, v32
	v_pk_mul_f32 v[18:19], v[32:33], v[18:19] op_sel:[1,0]
	v_pk_mul_f32 v[12:13], v[32:33], v[12:13] op_sel:[1,0]
	v_cvt_pk_bf16_f32 v10, v10, v11
	v_pk_fma_f32 v[16:17], v[194:195], v[12:13], v[202:203]
	v_pk_fma_f32 v[12:13], v[192:193], v[18:19], v[200:201]
	v_cvt_pk_bf16_f32 v11, v20, v21
	v_cvt_pk_bf16_f32 v12, v12, v13
	v_cvt_pk_bf16_f32 v13, v16, v17
	v_mad_u64_u32 v[14:15], s[18:19], v30, s89, v[0:1]
	ds_write_b128 v14, v[10:13] offset:36864
	s_or_b64 exec, exec, s[16:17]
	s_and_saveexec_b64 s[16:17], s[42:43]
	s_cbranch_execz .LBB0_486
.LBB0_509:
	v_add_u32_e32 v10, 0x1b400, v39
	ds_read_b64 v[26:27], v10
	v_lshlrev_b32_e32 v28, 16, v6
	v_and_b32_e32 v29, 0xffff0000, v6
	v_lshlrev_b32_e32 v6, 16, v7
	v_and_b32_e32 v7, 0xffff0000, v7
	v_lshlrev_b32_e32 v32, 16, v8
	v_and_b32_e32 v33, 0xffff0000, v8
	v_lshlrev_b32_e32 v39, 16, v9
	v_and_b32_e32 v40, 0xffff0000, v9
	s_waitcnt lgkmcnt(0)
	v_sub_f32_e32 v7, v7, v26
	v_sub_f32_e32 v6, v6, v26
	v_sub_f32_e32 v9, v29, v26
	v_sub_f32_e32 v8, v28, v26
	v_pk_mul_f32 v[8:9], v[26:27], v[8:9] op_sel:[1,0]
	v_pk_mul_f32 v[6:7], v[26:27], v[6:7] op_sel:[1,0]
	s_waitcnt vmcnt(5)
	v_pk_fma_f32 v[16:17], v[198:199], v[6:7], v[206:207]
	v_pk_fma_f32 v[6:7], v[196:197], v[8:9], v[204:205]
	v_sub_f32_e32 v9, v40, v26
	v_sub_f32_e32 v8, v39, v26
	v_sub_f32_e32 v15, v33, v26
	v_sub_f32_e32 v14, v32, v26
	v_pk_mul_f32 v[14:15], v[26:27], v[14:15] op_sel:[1,0]
	v_pk_mul_f32 v[8:9], v[26:27], v[8:9] op_sel:[1,0]
	v_cvt_pk_bf16_f32 v6, v6, v7
	v_pk_fma_f32 v[12:13], v[194:195], v[8:9], v[202:203]
	v_pk_fma_f32 v[8:9], v[192:193], v[14:15], v[200:201]
	v_cvt_pk_bf16_f32 v7, v16, v17
	v_cvt_pk_bf16_f32 v8, v8, v9
	v_cvt_pk_bf16_f32 v9, v12, v13
	v_mad_u64_u32 v[10:11], s[18:19], v38, s89, v[0:1]
	ds_write_b128 v10, v[6:9] offset:55296
	s_or_b64 exec, exec, s[16:17]
	s_and_saveexec_b64 s[16:17], s[40:41]
	s_cbranch_execnz .LBB0_487
	s_branch .LBB0_488
